# attention: chunk addresses from per-item base pointers + scalar chunk offset (was ~35 VALU per step)
# speedup vs baseline: 1.0387x; 1.0043x over previous
.LBB0_470:
	s_andn2_saveexec_b64 s[4:5], s[4:5]
	v_lshlrev_b64 v[2:3], 16, v[34:35]
	v_lshl_add_u64 v[4:5], s[80:81], 0, v[2:3]
	s_mov_b64 s[6:7], 0x2000
	v_lshl_add_u64 v[2:3], s[92:93], 0, v[2:3]
	v_lshl_add_u64 v[36:37], v[4:5], 0, s[6:7]
	v_lshl_add_u64 v[38:39], v[2:3], 0, s[6:7]
	s_or_b64 exec, exec, s[4:5]
	v_mov_b32_e32 v16, v133
	v_mov_b32_e32 v17, v133
	v_mov_b32_e32 v2, v133
	v_mov_b32_e32 v3, v133
	v_mov_b32_e32 v4, v133
	v_mov_b32_e32 v5, v133
	v_mov_b32_e32 v6, v133
	v_mov_b32_e32 v7, v133
	v_mov_b32_e32 v8, v133
	v_mov_b32_e32 v9, v133
	v_mov_b32_e32 v10, v133
	v_mov_b32_e32 v11, v133
	v_mov_b32_e32 v12, v133
	v_mov_b32_e32 v13, v133
	v_mov_b32_e32 v14, v133
	v_mov_b32_e32 v15, v133
	v_mov_b64_e32 v[32:33], v[16:17]
	v_cmp_lt_i32_e32 vcc, 0, v183
	v_mov_b32_e32 v149, 0
	v_mov_b64_e32 v[30:31], v[14:15]
	v_mov_b64_e32 v[28:29], v[12:13]
	v_mov_b64_e32 v[26:27], v[10:11]
	v_mov_b64_e32 v[24:25], v[8:9]
	v_mov_b64_e32 v[22:23], v[6:7]
	v_mov_b64_e32 v[20:21], v[4:5]
	v_mov_b64_e32 v[18:19], v[2:3]
	s_and_saveexec_b64 s[82:83], vcc
	s_cbranch_execz .LBB0_456
	v_lshl_add_u64 v[2:3], v[38:39], 0, v[142:143]
	v_lshl_add_u64 v[2:3], v[2:3], 0, v[138:139]
	v_lshl_add_u64 v[4:5], v[38:39], 0, v[132:133]
	v_lshl_add_u64 v[4:5], v[4:5], 0, v[138:139]
	global_load_dwordx4 v[114:117], v[2:3], off
	global_load_dwordx4 v[118:121], v[4:5], off
	v_lshl_add_u64 v[2:3], v[36:37], 0, v[142:143]
	v_lshl_add_u64 v[2:3], v[2:3], 0, v[138:139]
	v_lshl_add_u64 v[4:5], v[36:37], 0, v[132:133]
	v_lshl_add_u64 v[4:5], v[4:5], 0, v[138:139]
	global_load_dwordx4 v[122:125], v[2:3], off
	global_load_dwordx4 v[126:129], v[4:5], off
	v_lshlrev_b64 v[2:3], 16, v[34:35]
	v_lshl_add_u64 v[156:157], s[80:81], 0, v[2:3]
	v_lshl_add_u64 v[158:159], s[92:93], 0, v[2:3]
	v_sub_u32_e32 v2, v171, v42
	v_lshl_add_u32 v187, v2, 2, v160
	v_sub_u32_e32 v2, v171, v41
	v_and_b32_e32 v3, -16, v2
	s_movk_i32 s3, 0xffe0
	v_cmp_eq_u32_e64 s[6:7], s3, v3
	s_movk_i32 s3, 0xffef
	v_add_u32_e32 v4, 1, v2
	v_cmp_lt_u32_e64 s[38:39], s3, v2
	s_movk_i32 s3, 0xffd0
	v_cmp_gt_u32_e64 s[8:9], 16, v4
	v_add_u32_e32 v4, 33, v2
	v_cmp_eq_u32_e64 s[40:41], s3, v3
	v_add_u32_e32 v3, 17, v2
	v_cmp_gt_u32_e64 s[10:11], 16, v4
	v_add_u32_e32 v4, 2, v2
	v_cmp_gt_u32_e64 s[42:43], 16, v3
	v_add_u32_e32 v3, 49, v2
	v_cmp_gt_u32_e64 s[12:13], 16, v4
	v_add_u32_e32 v4, 34, v2
	v_cmp_gt_u32_e64 s[44:45], 16, v3
	v_add_u32_e32 v3, 18, v2
	v_cmp_gt_u32_e64 s[14:15], 16, v4
	v_add_u32_e32 v4, 3, v2
	v_cmp_gt_u32_e64 s[46:47], 16, v3
	v_add_u32_e32 v3, 50, v2
	v_cmp_gt_u32_e64 s[16:17], 16, v4
	v_add_u32_e32 v4, 35, v2
	v_cmp_gt_u32_e64 s[48:49], 16, v3
	v_add_u32_e32 v3, 19, v2
	v_cmp_gt_u32_e64 s[18:19], 16, v4
	v_add_u32_e32 v4, 8, v2
	v_cmp_gt_u32_e64 s[50:51], 16, v3
	v_add_u32_e32 v3, 51, v2
	v_cmp_gt_u32_e64 s[20:21], 16, v4
	v_add_u32_e32 v4, 40, v2
	v_cmp_gt_u32_e64 s[52:53], 16, v3
	v_add_u32_e32 v3, 24, v2
	v_cmp_gt_u32_e64 s[22:23], 16, v4
	v_add_u32_e32 v4, 9, v2
	v_cmp_gt_u32_e64 s[54:55], 16, v3
	v_add_u32_e32 v3, 56, v2
	v_cmp_gt_u32_e64 s[24:25], 16, v4
	v_add_u32_e32 v4, 41, v2
	v_cmp_gt_u32_e64 s[56:57], 16, v3
	v_add_u32_e32 v3, 25, v2
	v_cmp_gt_u32_e64 s[26:27], 16, v4
	v_add_u32_e32 v4, 10, v2
	v_cmp_gt_u32_e64 s[58:59], 16, v3
	v_add_u32_e32 v3, 57, v2
	v_cmp_gt_u32_e64 s[28:29], 16, v4
	v_add_u32_e32 v4, 42, v2
	v_cmp_gt_u32_e64 s[60:61], 16, v3
	v_add_u32_e32 v3, 26, v2
	v_cmp_gt_u32_e64 s[30:31], 16, v4
	v_add_u32_e32 v4, 11, v2
	v_cmp_gt_u32_e64 s[62:63], 16, v3
	v_add_u32_e32 v3, 58, v2
	v_cmp_gt_u32_e64 s[4:5], 16, v2
	v_cmp_gt_u32_e64 s[34:35], 16, v4
	v_add_u32_e32 v4, 43, v2
	v_cmp_gt_u32_e64 s[64:65], 16, v3
	v_add_u32_e32 v3, 27, v2
	v_add_u32_e32 v2, 59, v2
	v_cmp_gt_u32_e64 s[66:67], 16, v3
	v_cmp_gt_u32_e64 s[68:69], 16, v2
	v_mul_u32_u24_e32 v2, 31, v145
	v_mul_u32_u24_e32 v3, 31, v40
	v_sub_u32_e32 v2, v2, v3
	v_mov_b32_e32 v16, v133
	v_mov_b32_e32 v17, v133
	v_cmp_gt_u32_e64 s[36:37], 16, v4
	v_subrev_u32_e32 v188, 31, v2
	v_mov_b32_e32 v2, v133
	v_mov_b32_e32 v3, v133
	v_mov_b32_e32 v4, v133
	v_mov_b32_e32 v5, v133
	v_mov_b32_e32 v6, v133
	v_mov_b32_e32 v7, v133
	v_mov_b32_e32 v8, v133
	v_mov_b32_e32 v9, v133
	v_mov_b32_e32 v10, v133
	v_mov_b32_e32 v11, v133
	v_mov_b32_e32 v12, v133
	v_mov_b32_e32 v13, v133
	v_mov_b32_e32 v14, v133
	v_mov_b32_e32 v15, v133
	v_mov_b64_e32 v[32:33], v[16:17]
	v_add_u32_e32 v185, -1, v183
	v_mul_hi_u32_u24_e32 v153, 0x6000, v184
	v_mul_u32_u24_e32 v152, 0x6000, v184
	v_mul_hi_u32_u24_e32 v155, 0x180, v184
	v_mul_u32_u24_e32 v154, 0x180, v184
	v_add_u32_e32 v186, 8, v182
	v_add_u32_e32 v189, -8, v145
	s_mov_b32 s3, 0
	v_mov_b32_e32 v190, 0xff800000
	v_mov_b32_e32 v149, 0
	s_mov_b64 s[70:71], 0
	s_xor_b64 s[86:87], s[0:1], -1
	v_mov_b64_e32 v[30:31], v[14:15]
	v_mov_b64_e32 v[28:29], v[12:13]
	v_mov_b64_e32 v[26:27], v[10:11]
	v_mov_b64_e32 v[24:25], v[8:9]
	v_mov_b64_e32 v[22:23], v[6:7]
	v_mov_b64_e32 v[20:21], v[4:5]
	v_mov_b64_e32 v[18:19], v[2:3]
	v_mov_b32_e32 v36, 0
	v_mov_b32_e32 v38, 0
	s_mov_b64 s[72:73], s[86:87]
	s_and_saveexec_b64 s[76:77], s[72:73]
	s_xor_b64 s[72:73], exec, s[76:77]
	s_cbranch_execz .Laddr478_a
	v_add_u32_e32 v34, v36, v145
	v_lshl_add_u32 v34, v34, 6, v181
	v_cndmask_b32_e64 v34, v38, v34, s[0:1]
	v_add_u32_e32 v36, v34, v148
	v_ashrrev_i32_e32 v37, 31, v36
	v_lshl_add_u64 v[34:35], v[152:153], 0, v[36:37]
	v_ashrrev_i32_e32 v36, 6, v36
	v_lshlrev_b64 v[34:35], 7, v[34:35]
	v_ashrrev_i32_e32 v37, 31, v36
	v_lshl_add_u64 v[34:35], s[88:89], 0, v[34:35]
	v_lshl_add_u64 v[36:37], v[154:155], 0, v[36:37]
.Laddr478_a:
	s_or_saveexec_b64 s[72:73], s[72:73]
	v_mov_b64_e32 v[40:41], s[90:91]
	s_xor_b64 exec, exec, s[72:73]
	v_ashrrev_i32_e32 v39, 31, v38
	v_lshlrev_b64 v[34:35], 7, v[38:39]
	v_lshl_add_u64 v[34:35], v[156:157], 0, v[34:35]
	v_ashrrev_i32_e32 v37, 31, v36
	v_mov_b64_e32 v[40:41], v[158:159]
	s_or_b64 exec, exec, s[72:73]
	v_lshlrev_b64 v[36:37], 13, v[36:37]
	v_lshl_add_u64 v[36:37], v[40:41], 0, v[36:37]
	v_mov_b32_e32 v242, v34
	v_mov_b32_e32 v243, v35
	v_mov_b32_e32 v248, v36
	v_mov_b32_e32 v249, v37
	v_mov_b32_e32 v36, 8
	v_mov_b32_e32 v38, 512
	s_mov_b64 s[72:73], exec
	s_and_saveexec_b64 s[76:77], s[72:73]
	s_xor_b64 s[72:73], exec, s[76:77]
	s_cbranch_execz .Laddr478_b
	v_add_u32_e32 v34, v36, v145
	v_lshl_add_u32 v34, v34, 6, v181
	v_cndmask_b32_e64 v34, v38, v34, s[0:1]
	v_add_u32_e32 v36, v34, v148
	v_ashrrev_i32_e32 v37, 31, v36
	v_lshl_add_u64 v[34:35], v[152:153], 0, v[36:37]
	v_ashrrev_i32_e32 v36, 6, v36
	v_lshlrev_b64 v[34:35], 7, v[34:35]
	v_ashrrev_i32_e32 v37, 31, v36
	v_lshl_add_u64 v[34:35], s[88:89], 0, v[34:35]
	v_lshl_add_u64 v[36:37], v[154:155], 0, v[36:37]
.Laddr478_b:
	s_or_saveexec_b64 s[72:73], s[72:73]
	v_mov_b64_e32 v[40:41], s[90:91]
	s_xor_b64 exec, exec, s[72:73]
	v_ashrrev_i32_e32 v39, 31, v38
	v_lshlrev_b64 v[34:35], 7, v[38:39]
	v_lshl_add_u64 v[34:35], v[156:157], 0, v[34:35]
	v_ashrrev_i32_e32 v37, 31, v36
	v_mov_b64_e32 v[40:41], v[158:159]
	s_or_b64 exec, exec, s[72:73]
	v_lshlrev_b64 v[36:37], 13, v[36:37]
	v_lshl_add_u64 v[36:37], v[40:41], 0, v[36:37]
	v_cndmask_b32_e64 v250, v242, v34, s[0:1]
	v_cndmask_b32_e64 v251, v243, v35, s[0:1]
	v_cndmask_b32_e64 v252, v248, v36, s[0:1]
	v_cndmask_b32_e64 v253, v249, v37, s[0:1]
	s_mov_b64 s[98:99], 0x800
	v_lshl_add_u64 v[254:255], v[132:133], 0, v[138:139]
	v_lshl_add_u64 v[254:255], v[254:255], 0, s[98:99]
	v_lshl_add_u64 v[242:243], v[242:243], 0, v[254:255]
	v_lshl_add_u64 v[248:249], v[248:249], 0, v[254:255]
	v_lshl_add_u64 v[250:251], v[250:251], 0, v[254:255]
	v_lshl_add_u64 v[252:253], v[252:253], 0, v[254:255]
	v_readfirstlane_b32 s100, v183
	s_branch .LBB0_476

.Lpv_even:
	v_pk_add_f32 v[50:51], v[50:51], v[190:191] op_sel_hi:[1,0] neg_lo:[0,1] neg_hi:[0,1]
	v_pk_add_f32 v[52:53], v[52:53], v[190:191] op_sel_hi:[1,0] neg_lo:[0,1] neg_hi:[0,1]
	v_pk_add_f32 v[54:55], v[54:55], v[190:191] op_sel_hi:[1,0] neg_lo:[0,1] neg_hi:[0,1]
	v_pk_add_f32 v[56:57], v[56:57], v[190:191] op_sel_hi:[1,0] neg_lo:[0,1] neg_hi:[0,1]
	v_exp_f32_e32 v50, v50
	v_exp_f32_e32 v51, v51
	v_exp_f32_e32 v52, v52
	v_exp_f32_e32 v53, v53
	v_exp_f32_e32 v54, v54
	v_exp_f32_e32 v55, v55
	v_exp_f32_e32 v56, v56
	v_exp_f32_e32 v57, v57
	v_cvt_pk_bf16_f32 v70, v50, v51
	v_cvt_pk_bf16_f32 v71, v52, v53
	v_cvt_pk_bf16_f32 v72, v54, v55
	v_cvt_pk_bf16_f32 v73, v56, v57
	v_mov_b32_e32 v68, v50
	v_mov_b32_e32 v69, v51
	v_pk_add_f32 v[68:69], v[68:69], v[52:53]
	v_pk_add_f32 v[68:69], v[68:69], v[54:55]
	v_pk_add_f32 v[68:69], v[68:69], v[56:57]
	v_mfma_f32_32x32x16_bf16 v[2:17], v[192:195], v[70:73], v[2:17]
	v_mfma_f32_32x32x16_bf16 v[18:33], v[208:211], v[70:73], v[18:33]
	v_pk_add_f32 v[58:59], v[58:59], v[190:191] op_sel_hi:[1,0] neg_lo:[0,1] neg_hi:[0,1]
	v_pk_add_f32 v[60:61], v[60:61], v[190:191] op_sel_hi:[1,0] neg_lo:[0,1] neg_hi:[0,1]
	v_pk_add_f32 v[62:63], v[62:63], v[190:191] op_sel_hi:[1,0] neg_lo:[0,1] neg_hi:[0,1]
	v_pk_add_f32 v[64:65], v[64:65], v[190:191] op_sel_hi:[1,0] neg_lo:[0,1] neg_hi:[0,1]
	v_exp_f32_e32 v58, v58
	v_exp_f32_e32 v59, v59
	v_exp_f32_e32 v60, v60
	v_exp_f32_e32 v61, v61
	v_exp_f32_e32 v62, v62
	v_exp_f32_e32 v63, v63
	v_exp_f32_e32 v64, v64
	v_exp_f32_e32 v65, v65
	v_cvt_pk_bf16_f32 v74, v58, v59
	v_cvt_pk_bf16_f32 v75, v60, v61
	v_cvt_pk_bf16_f32 v76, v62, v63
	v_cvt_pk_bf16_f32 v77, v64, v65
	v_pk_add_f32 v[68:69], v[68:69], v[58:59]
	v_pk_add_f32 v[68:69], v[68:69], v[60:61]
	v_pk_add_f32 v[68:69], v[68:69], v[62:63]
	v_pk_add_f32 v[68:69], v[68:69], v[64:65]
	v_mfma_f32_32x32x16_bf16 v[2:17], v[196:199], v[74:77], v[2:17]
	v_mfma_f32_32x32x16_bf16 v[18:33], v[214:217], v[74:77], v[18:33]
	v_pk_add_f32 v[34:35], v[34:35], v[190:191] op_sel_hi:[1,0] neg_lo:[0,1] neg_hi:[0,1]
	v_pk_add_f32 v[36:37], v[36:37], v[190:191] op_sel_hi:[1,0] neg_lo:[0,1] neg_hi:[0,1]
	v_exp_f32_e32 v34, v34
	v_exp_f32_e32 v35, v35
	v_exp_f32_e32 v36, v36
	v_exp_f32_e32 v37, v37
	v_cvt_pk_bf16_f32 v78, v34, v35
	v_cvt_pk_bf16_f32 v79, v36, v37
	v_mov_b32_e32 v80, 0
	v_mov_b32_e32 v81, 0
	v_pk_add_f32 v[68:69], v[68:69], v[34:35]
	v_pk_add_f32 v[68:69], v[68:69], v[36:37]
	v_mfma_f32_32x32x16_bf16 v[2:17], v[200:203], v[78:81], v[2:17]
	v_mfma_f32_32x32x16_bf16 v[18:33], v[218:221], v[78:81], v[18:33]
	v_add_f32_e32 v68, v68, v69
	v_add_f32_e32 v149, v149, v68
	s_branch .LBB0_475

.Lpv_odd:
	v_pk_add_f32 v[62:63], v[62:63], v[190:191] op_sel_hi:[1,0] neg_lo:[0,1] neg_hi:[0,1]
	v_pk_add_f32 v[64:65], v[64:65], v[190:191] op_sel_hi:[1,0] neg_lo:[0,1] neg_hi:[0,1]
	v_exp_f32_e32 v62, v62
	v_exp_f32_e32 v63, v63
	v_exp_f32_e32 v64, v64
	v_exp_f32_e32 v65, v65
	v_mov_b32_e32 v74, 0
	v_mov_b32_e32 v75, 0
	v_cvt_pk_bf16_f32 v76, v62, v63
	v_cvt_pk_bf16_f32 v77, v64, v65
	v_mov_b32_e32 v68, v62
	v_mov_b32_e32 v69, v63
	v_pk_add_f32 v[68:69], v[68:69], v[64:65]
	v_mfma_f32_32x32x16_bf16 v[2:17], v[196:199], v[74:77], v[2:17]
	v_mfma_f32_32x32x16_bf16 v[18:33], v[214:217], v[74:77], v[18:33]
	v_pk_add_f32 v[34:35], v[34:35], v[190:191] op_sel_hi:[1,0] neg_lo:[0,1] neg_hi:[0,1]
	v_pk_add_f32 v[36:37], v[36:37], v[190:191] op_sel_hi:[1,0] neg_lo:[0,1] neg_hi:[0,1]
	v_pk_add_f32 v[38:39], v[38:39], v[190:191] op_sel_hi:[1,0] neg_lo:[0,1] neg_hi:[0,1]
	v_pk_add_f32 v[40:41], v[40:41], v[190:191] op_sel_hi:[1,0] neg_lo:[0,1] neg_hi:[0,1]
	v_exp_f32_e32 v34, v34
	v_exp_f32_e32 v35, v35
	v_exp_f32_e32 v36, v36
	v_exp_f32_e32 v37, v37
	v_exp_f32_e32 v38, v38
	v_exp_f32_e32 v39, v39
	v_exp_f32_e32 v40, v40
	v_exp_f32_e32 v41, v41
	v_cvt_pk_bf16_f32 v78, v34, v35
	v_cvt_pk_bf16_f32 v79, v36, v37
	v_cvt_pk_bf16_f32 v80, v38, v39
	v_cvt_pk_bf16_f32 v81, v40, v41
	v_pk_add_f32 v[68:69], v[68:69], v[34:35]
	v_pk_add_f32 v[68:69], v[68:69], v[36:37]
	v_pk_add_f32 v[68:69], v[68:69], v[38:39]
	v_pk_add_f32 v[68:69], v[68:69], v[40:41]
	v_mfma_f32_32x32x16_bf16 v[2:17], v[200:203], v[78:81], v[2:17]
	v_mfma_f32_32x32x16_bf16 v[18:33], v[218:221], v[78:81], v[18:33]
	v_pk_add_f32 v[42:43], v[42:43], v[190:191] op_sel_hi:[1,0] neg_lo:[0,1] neg_hi:[0,1]
	v_pk_add_f32 v[44:45], v[44:45], v[190:191] op_sel_hi:[1,0] neg_lo:[0,1] neg_hi:[0,1]
	v_pk_add_f32 v[46:47], v[46:47], v[190:191] op_sel_hi:[1,0] neg_lo:[0,1] neg_hi:[0,1]
	v_pk_add_f32 v[48:49], v[48:49], v[190:191] op_sel_hi:[1,0] neg_lo:[0,1] neg_hi:[0,1]
	v_exp_f32_e32 v42, v42
	v_exp_f32_e32 v43, v43
	v_exp_f32_e32 v44, v44
	v_exp_f32_e32 v45, v45
	v_exp_f32_e32 v46, v46
	v_exp_f32_e32 v47, v47
	v_exp_f32_e32 v48, v48
	v_exp_f32_e32 v49, v49
	v_cvt_pk_bf16_f32 v82, v42, v43
	v_cvt_pk_bf16_f32 v83, v44, v45
	v_cvt_pk_bf16_f32 v84, v46, v47
	v_cvt_pk_bf16_f32 v85, v48, v49
	v_pk_add_f32 v[68:69], v[68:69], v[42:43]
	v_pk_add_f32 v[68:69], v[68:69], v[44:45]
	v_pk_add_f32 v[68:69], v[68:69], v[46:47]
	v_pk_add_f32 v[68:69], v[68:69], v[48:49]
	v_mfma_f32_32x32x16_bf16 v[2:17], v[204:207], v[82:85], v[2:17]
	v_mfma_f32_32x32x16_bf16 v[18:33], v[222:225], v[82:85], v[18:33]
	v_add_f32_e32 v68, v68, v69
	v_add_f32_e32 v149, v149, v68
	s_branch .LBB0_475
.LBB0_474:
	v_pk_add_f32 v[50:51], v[50:51], v[190:191] op_sel_hi:[1,0] neg_lo:[0,1] neg_hi:[0,1]
	v_pk_add_f32 v[52:53], v[52:53], v[190:191] op_sel_hi:[1,0] neg_lo:[0,1] neg_hi:[0,1]
	v_pk_add_f32 v[54:55], v[54:55], v[190:191] op_sel_hi:[1,0] neg_lo:[0,1] neg_hi:[0,1]
	v_pk_add_f32 v[56:57], v[56:57], v[190:191] op_sel_hi:[1,0] neg_lo:[0,1] neg_hi:[0,1]
	v_exp_f32_e32 v50, v50
	v_exp_f32_e32 v51, v51
	v_exp_f32_e32 v52, v52
	v_exp_f32_e32 v53, v53
	v_exp_f32_e32 v54, v54
	v_exp_f32_e32 v55, v55
	v_exp_f32_e32 v56, v56
	v_exp_f32_e32 v57, v57
	v_cvt_pk_bf16_f32 v70, v50, v51
	v_cvt_pk_bf16_f32 v71, v52, v53
	v_cvt_pk_bf16_f32 v72, v54, v55
	v_pk_add_f32 v[58:59], v[58:59], v[190:191] op_sel_hi:[1,0] neg_lo:[0,1] neg_hi:[0,1]
	v_cvt_pk_bf16_f32 v73, v56, v57
	v_pk_add_f32 v[60:61], v[60:61], v[190:191] op_sel_hi:[1,0] neg_lo:[0,1] neg_hi:[0,1]
	v_pk_add_f32 v[62:63], v[62:63], v[190:191] op_sel_hi:[1,0] neg_lo:[0,1] neg_hi:[0,1]
	v_mfma_f32_32x32x16_bf16 v[2:17], v[192:195], v[70:73], v[2:17]
	v_mfma_f32_32x32x16_bf16 v[18:33], v[208:211], v[70:73], v[18:33]
	v_pk_add_f32 v[64:65], v[64:65], v[190:191] op_sel_hi:[1,0] neg_lo:[0,1] neg_hi:[0,1]
	v_exp_f32_e32 v58, v58
	v_exp_f32_e32 v59, v59
	v_exp_f32_e32 v60, v60
	v_exp_f32_e32 v61, v61
	v_exp_f32_e32 v62, v62
	v_exp_f32_e32 v63, v63
	v_exp_f32_e32 v64, v64
	v_exp_f32_e32 v65, v65
	v_pk_add_f32 v[66:67], v[50:51], v[52:53]
	v_pk_add_f32 v[66:67], v[66:67], v[54:55]
	v_pk_add_f32 v[66:67], v[66:67], v[56:57]
	v_cvt_pk_bf16_f32 v74, v58, v59
	v_cvt_pk_bf16_f32 v75, v60, v61
	v_cvt_pk_bf16_f32 v76, v62, v63
	v_pk_add_f32 v[34:35], v[34:35], v[190:191] op_sel_hi:[1,0] neg_lo:[0,1] neg_hi:[0,1]
	v_cvt_pk_bf16_f32 v77, v64, v65
	v_pk_add_f32 v[36:37], v[36:37], v[190:191] op_sel_hi:[1,0] neg_lo:[0,1] neg_hi:[0,1]
	v_pk_add_f32 v[38:39], v[38:39], v[190:191] op_sel_hi:[1,0] neg_lo:[0,1] neg_hi:[0,1]
	v_mfma_f32_32x32x16_bf16 v[2:17], v[196:199], v[74:77], v[2:17]
	v_mfma_f32_32x32x16_bf16 v[18:33], v[214:217], v[74:77], v[18:33]
	v_pk_add_f32 v[40:41], v[40:41], v[190:191] op_sel_hi:[1,0] neg_lo:[0,1] neg_hi:[0,1]
	v_exp_f32_e32 v34, v34
	v_exp_f32_e32 v35, v35
	v_exp_f32_e32 v36, v36
	v_exp_f32_e32 v37, v37
	v_exp_f32_e32 v38, v38
	v_exp_f32_e32 v39, v39
	v_exp_f32_e32 v40, v40
	v_exp_f32_e32 v41, v41
	v_pk_add_f32 v[66:67], v[66:67], v[58:59]
	v_pk_add_f32 v[66:67], v[66:67], v[60:61]
	v_pk_add_f32 v[66:67], v[66:67], v[62:63]
	v_pk_add_f32 v[66:67], v[66:67], v[64:65]
	v_cvt_pk_bf16_f32 v78, v34, v35
	v_cvt_pk_bf16_f32 v79, v36, v37
	v_cvt_pk_bf16_f32 v80, v38, v39
	v_pk_add_f32 v[42:43], v[42:43], v[190:191] op_sel_hi:[1,0] neg_lo:[0,1] neg_hi:[0,1]
	v_cvt_pk_bf16_f32 v81, v40, v41
	v_pk_add_f32 v[44:45], v[44:45], v[190:191] op_sel_hi:[1,0] neg_lo:[0,1] neg_hi:[0,1]
	v_pk_add_f32 v[46:47], v[46:47], v[190:191] op_sel_hi:[1,0] neg_lo:[0,1] neg_hi:[0,1]
	v_mfma_f32_32x32x16_bf16 v[2:17], v[200:203], v[78:81], v[2:17]
	v_mfma_f32_32x32x16_bf16 v[18:33], v[218:221], v[78:81], v[18:33]
	v_pk_add_f32 v[48:49], v[48:49], v[190:191] op_sel_hi:[1,0] neg_lo:[0,1] neg_hi:[0,1]
	v_exp_f32_e32 v42, v42
	v_exp_f32_e32 v43, v43
	v_exp_f32_e32 v44, v44
	v_exp_f32_e32 v45, v45
	v_exp_f32_e32 v46, v46
	v_exp_f32_e32 v47, v47
	v_exp_f32_e32 v48, v48
	v_exp_f32_e32 v49, v49
	v_pk_add_f32 v[68:69], v[34:35], v[36:37]
	v_pk_add_f32 v[68:69], v[68:69], v[38:39]
	v_pk_add_f32 v[68:69], v[68:69], v[40:41]
	v_cvt_pk_bf16_f32 v82, v42, v43
	v_cvt_pk_bf16_f32 v83, v44, v45
	v_cvt_pk_bf16_f32 v84, v46, v47
	v_cvt_pk_bf16_f32 v85, v48, v49
	v_pk_add_f32 v[68:69], v[68:69], v[42:43]
	v_pk_add_f32 v[68:69], v[68:69], v[44:45]
	v_mfma_f32_32x32x16_bf16 v[2:17], v[204:207], v[82:85], v[2:17]
	v_mfma_f32_32x32x16_bf16 v[18:33], v[222:225], v[82:85], v[18:33]
	v_pk_add_f32 v[68:69], v[68:69], v[46:47]
	v_pk_add_f32 v[68:69], v[68:69], v[48:49]
	v_pk_add_f32 v[66:67], v[66:67], v[68:69]
	v_add_f32_e32 v66, v66, v67
	v_add_f32_e32 v149, v149, v66

.LBB0_476:
	s_add_i32 s79, s3, 1
	s_bitcmp1_b32 s79, 0
	s_cselect_b32 s72, 0x4800, 0
	v_add_u32_e32 v34, s72, v160
	v_add_u32_e32 v35, v34, v168
	v_add_u32_e32 v36, v35, v169
	v_add_u32_e32 v34, v34, v170
	s_waitcnt lgkmcnt(0)
	s_barrier
	s_waitcnt vmcnt(0)
	ds_write_b128 v36, v[126:129]
	v_add_u32_e32 v36, v34, v169
	ds_write_b128 v36, v[122:125]
	v_add_u32_e32 v35, v35, v167
	v_add_u32_e32 v34, v34, v167
	v_add_u32_e32 v35, 0x2000, v35
	v_add_u32_e32 v34, 0x2000, v34
	ds_write2_b64 v35, v[118:119], v[120:121] offset0:128 offset1:130
	ds_write2_b64 v34, v[114:115], v[116:117] offset0:128 offset1:130
	s_add_i32 s98, s79, 1
	s_add_i32 s99, s100, -1
	s_min_u32 s98, s98, s99
	s_cmp_lt_u32 s100, 9
	s_cbranch_scc1 .Lg_r2
	s_cmp_lt_u32 s98, 8
	s_cbranch_scc1 .Lg_r1
	s_sub_u32 s98, s98, 8
.Lg_r2:
	s_lshl_b32 s98, s98, 13
	s_mov_b32 s99, 0
	v_lshl_add_u64 v[34:35], v[250:251], 0, s[98:99]
	v_lshl_add_u64 v[36:37], v[252:253], 0, s[98:99]
	s_branch .Lg_ld
.Lg_r1:
	s_lshl_b32 s98, s98, 13
	s_mov_b32 s99, 0
	v_lshl_add_u64 v[34:35], v[242:243], 0, s[98:99]
	v_lshl_add_u64 v[36:37], v[248:249], 0, s[98:99]
.Lg_ld:
	global_load_dwordx4 v[126:129], v[34:35], off offset:-2048
	global_load_dwordx4 v[122:125], v[34:35], off offset:2048
	global_load_dwordx4 v[118:121], v[36:37], off offset:-2048
	global_load_dwordx4 v[114:117], v[36:37], off offset:2048
	s_cmp_gt_u32 s3, 7
	s_cselect_b64 s[72:73], -1, 0
	s_and_b64 s[94:95], s[0:1], s[72:73]
	v_mov_b32_e32 v66, 0
	s_mov_b64 vcc, -1
	s_and_saveexec_b64 s[76:77], s[94:95]
	v_add_u32_e32 v34, s3, v189
	v_cmp_ge_i32_e32 vcc, v34, v182
	v_cmp_lt_i32_e64 s[72:73], v34, v186
	s_and_b64 s[72:73], vcc, s[72:73]
	s_orn2_b64 vcc, s[72:73], exec
	v_mov_b32_e32 v66, v188
	s_or_b64 exec, exec, s[76:77]
	s_and_saveexec_b64 s[72:73], vcc
	s_cbranch_execz .LBB0_475
	s_bitcmp1_b32 s3, 0
	s_cselect_b32 s3, 0x4800, 0
	v_add_u32_e32 v137, s3, v173
	ds_read_b128 v[192:195], v137
	ds_read_b128 v[208:211], v137 offset:4608
	ds_read_b128 v[196:199], v137 offset:32
	ds_read_b128 v[214:217], v137 offset:4640
	ds_read_b128 v[200:203], v137 offset:64
	ds_read_b128 v[218:221], v137 offset:4672
	ds_read_b128 v[204:207], v137 offset:96
	ds_read_b128 v[222:225], v137 offset:4704
	s_waitcnt lgkmcnt(6)
	v_mfma_f32_32x32x16_bf16 v[50:65], v[192:195], v[98:101], 0
	v_mfma_f32_32x32x16_bf16 v[34:49], v[208:211], v[98:101], 0
	s_waitcnt lgkmcnt(4)
	v_mfma_f32_32x32x16_bf16 v[50:65], v[196:199], v[102:105], v[50:65]
	v_mfma_f32_32x32x16_bf16 v[34:49], v[214:217], v[102:105], v[34:49]
	s_waitcnt lgkmcnt(2)
	v_mfma_f32_32x32x16_bf16 v[50:65], v[200:203], v[106:109], v[50:65]
	v_mfma_f32_32x32x16_bf16 v[34:49], v[218:221], v[106:109], v[34:49]
	s_waitcnt lgkmcnt(0)
	v_mfma_f32_32x32x16_bf16 v[50:65], v[204:207], v[110:113], v[50:65]
	v_mfma_f32_32x32x16_bf16 v[34:49], v[222:225], v[110:113], v[34:49]
	ds_read_b128 v[192:195], v137 offset:9216
	ds_read_b128 v[208:211], v137 offset:13824
	ds_read_b128 v[196:199], v137 offset:9248
	ds_read_b128 v[214:217], v137 offset:13856
	ds_read_b128 v[200:203], v137 offset:9280
	ds_read_b128 v[218:221], v137 offset:13888
	ds_read_b128 v[204:207], v137 offset:9312
	ds_read_b128 v[222:225], v137 offset:13920
	s_and_saveexec_b64 vcc, s[94:95]
	s_cbranch_execz .LBB0_549
	v_lshl_add_u32 v141, v66, 2, v187
	v_add_u32_e32 v141, 0x903c, v141
	v_mov_b32_e32 v246, 0xff800000
	v_readfirstlane_b32 s98, v212
	s_nop 0
	s_bitcmp1_b32 s98, 6
	s_cbranch_scc1 .Lwin_odd
	s_branch .Lwin_even

	.amdhsa_kernel _Z4mega1P
		.amdhsa_group_segment_fixed_size 147472
		.amdhsa_private_segment_fixed_size 0
		.amdhsa_kernarg_size 488
		.amdhsa_user_sgpr_count 2
		.amdhsa_user_sgpr_dispatch_ptr 0
		.amdhsa_user_sgpr_queue_ptr 0
		.amdhsa_user_sgpr_kernarg_segment_ptr 1
		.amdhsa_user_sgpr_dispatch_id 0
		.amdhsa_user_sgpr_kernarg_preload_length 0
		.amdhsa_user_sgpr_kernarg_preload_offset 0
		.amdhsa_user_sgpr_private_segment_size 0
		.amdhsa_uses_dynamic_stack 0
		.amdhsa_enable_private_segment 0
		.amdhsa_system_sgpr_workgroup_id_x 1
		.amdhsa_system_sgpr_workgroup_id_y 0
		.amdhsa_system_sgpr_workgroup_id_z 0
		.amdhsa_system_sgpr_workgroup_info 0
		.amdhsa_system_vgpr_workitem_id 2
		.amdhsa_next_free_vgpr 256
		.amdhsa_next_free_sgpr 102
		.amdhsa_accum_offset 256
		.amdhsa_reserve_vcc 1
		.amdhsa_float_round_mode_32 0
		.amdhsa_float_round_mode_16_64 0
		.amdhsa_float_denorm_mode_32 3
		.amdhsa_float_denorm_mode_16_64 3
		.amdhsa_dx10_clamp 1
		.amdhsa_ieee_mode 1
		.amdhsa_fp16_overflow 0
		.amdhsa_tg_split 0
		.amdhsa_exception_fp_ieee_invalid_op 0
		.amdhsa_exception_fp_denorm_src 0
		.amdhsa_exception_fp_ieee_div_zero 0
		.amdhsa_exception_fp_ieee_overflow 0
		.amdhsa_exception_fp_ieee_underflow 0
		.amdhsa_exception_fp_ieee_inexact 0
		.amdhsa_exception_int_div_zero 0
	.end_amdhsa_kernel

amdhsa.kernels:
  - .agpr_count:     0
    .args:
      - .offset:         0
        .size:           232
        .value_kind:     by_value
      - .offset:         232
        .size:           4
        .value_kind:     hidden_block_count_x
      - .offset:         236
        .size:           4
        .value_kind:     hidden_block_count_y
      - .offset:         240
        .size:           4
        .value_kind:     hidden_block_count_z
      - .offset:         244
        .size:           2
        .value_kind:     hidden_group_size_x
      - .offset:         246
        .size:           2
        .value_kind:     hidden_group_size_y
      - .offset:         248
        .size:           2
        .value_kind:     hidden_group_size_z
      - .offset:         250
        .size:           2
        .value_kind:     hidden_remainder_x
      - .offset:         252
        .size:           2
        .value_kind:     hidden_remainder_y
      - .offset:         254
        .size:           2
        .value_kind:     hidden_remainder_z
      - .offset:         272
        .size:           8
        .value_kind:     hidden_global_offset_x
      - .offset:         280
        .size:           8
        .value_kind:     hidden_global_offset_y
      - .offset:         288
        .size:           8
        .value_kind:     hidden_global_offset_z
      - .offset:         296
        .size:           2
        .value_kind:     hidden_grid_dims
      - .offset:         320
        .size:           8
        .value_kind:     hidden_multigrid_sync_arg
    .group_segment_fixed_size: 147472
    .kernarg_segment_align: 8
    .kernarg_segment_size: 488
    .language:       OpenCL C
    .language_version:
      - 2
      - 0
    .max_flat_workgroup_size: 512
    .name:           _Z4mega1P
    .private_segment_fixed_size: 0
    .sgpr_count:     108
    .sgpr_spill_count: 74
    .symbol:         _Z4mega1P.kd
    .uniform_work_group_size: 1
    .uses_dynamic_stack: false
    .vgpr_count:     256
    .vgpr_spill_count: 0
    .wavefront_size: 64
